# tile-stop min: scalar readlane waterfall loop replaced by all-lane LDS atomic min
# baseline (speedup 1.0000x reference)
.LBB0_572:
	v_mov_b32_e32 v1, s71
	ds_min_i32 v1, v0
